# P0 weight conversion (no-gain variants): two-trip staging loop unrolled, second trip's 16 loads issued before the first trip's LDS writes (32 loads in flight)
# baseline (speedup 1.0000x reference)
; __device__ __forceinline__ void conv_item(const float* W, int K, int N, bf16* WT, const float* gain, int mapmode, bool f16, LAS float* scr, int item, int lane) {
;     ...
; #pragma unroll 16
;     for (int i = 0; i < 32; ++i) { const int kk = 2 * i + (lane >> 5); float v = __builtin_nontemporal_load(W + (size_t)(k0 + kk) * N + n0 + (lane & 31)); if (gain) v *= gain[k0 + kk]; scr[kk * 33 + (lane & 31)] = v; }
.LBB0_46:
	v_add_u32_e32 v24, s17, v22
	v_ashrrev_i32_e32 v25, 31, v24
	v_add_u32_e32 v26, 2, v24
	v_add_u32_e32 v28, 4, v24
	v_add_u32_e32 v30, 6, v24
	v_add_u32_e32 v32, 8, v24
	v_add_u32_e32 v34, 10, v24
	v_add_u32_e32 v36, 12, v24
	v_add_u32_e32 v38, 14, v24
	v_add_u32_e32 v40, 16, v24
	v_add_u32_e32 v42, 18, v24
	v_add_u32_e32 v44, 20, v24
	v_add_u32_e32 v46, 22, v24
	v_add_u32_e32 v48, 24, v24
	v_add_u32_e32 v50, 26, v24
	v_add_u32_e32 v52, 28, v24
	v_add_u32_e32 v54, 30, v24
	v_lshlrev_b64 v[24:25], 12, v[24:25]
	v_ashrrev_i32_e32 v27, 31, v26
	v_ashrrev_i32_e32 v29, 31, v28
	v_ashrrev_i32_e32 v31, 31, v30
	v_ashrrev_i32_e32 v33, 31, v32
	v_ashrrev_i32_e32 v35, 31, v34
	v_ashrrev_i32_e32 v37, 31, v36
	v_ashrrev_i32_e32 v39, 31, v38
	v_ashrrev_i32_e32 v41, 31, v40
	v_ashrrev_i32_e32 v43, 31, v42
	v_ashrrev_i32_e32 v45, 31, v44
	v_ashrrev_i32_e32 v47, 31, v46
	v_ashrrev_i32_e32 v49, 31, v48
	v_ashrrev_i32_e32 v51, 31, v50
	v_ashrrev_i32_e32 v53, 31, v52
	v_ashrrev_i32_e32 v55, 31, v54
	v_lshl_add_u64 v[24:25], v[20:21], 0, v[24:25]
	v_lshlrev_b64 v[26:27], 12, v[26:27]
	v_lshlrev_b64 v[28:29], 12, v[28:29]
	v_lshlrev_b64 v[30:31], 12, v[30:31]
	v_lshlrev_b64 v[32:33], 12, v[32:33]
	v_lshlrev_b64 v[34:35], 12, v[34:35]
	v_lshlrev_b64 v[36:37], 12, v[36:37]
	v_lshlrev_b64 v[38:39], 12, v[38:39]
	v_lshlrev_b64 v[40:41], 12, v[40:41]
	v_lshlrev_b64 v[42:43], 12, v[42:43]
	v_lshlrev_b64 v[44:45], 12, v[44:45]
	v_lshlrev_b64 v[46:47], 12, v[46:47]
	v_lshlrev_b64 v[48:49], 12, v[48:49]
	v_lshlrev_b64 v[50:51], 12, v[50:51]
	v_lshlrev_b64 v[52:53], 12, v[52:53]
	v_lshlrev_b64 v[54:55], 12, v[54:55]
	v_lshl_add_u64 v[26:27], v[20:21], 0, v[26:27]
	v_lshl_add_u64 v[28:29], v[20:21], 0, v[28:29]
	v_lshl_add_u64 v[30:31], v[20:21], 0, v[30:31]
	v_lshl_add_u64 v[32:33], v[20:21], 0, v[32:33]
	v_lshl_add_u64 v[34:35], v[20:21], 0, v[34:35]
	v_lshl_add_u64 v[36:37], v[20:21], 0, v[36:37]
	v_lshl_add_u64 v[38:39], v[20:21], 0, v[38:39]
	v_lshl_add_u64 v[40:41], v[20:21], 0, v[40:41]
	v_lshl_add_u64 v[42:43], v[20:21], 0, v[42:43]
	v_lshl_add_u64 v[44:45], v[20:21], 0, v[44:45]
	v_lshl_add_u64 v[46:47], v[20:21], 0, v[46:47]
	v_lshl_add_u64 v[48:49], v[20:21], 0, v[48:49]
	v_lshl_add_u64 v[50:51], v[20:21], 0, v[50:51]
	v_lshl_add_u64 v[52:53], v[20:21], 0, v[52:53]
	v_lshl_add_u64 v[54:55], v[20:21], 0, v[54:55]
	global_load_dword v56, v[24:25], off nt
	global_load_dword v57, v[26:27], off nt
	global_load_dword v58, v[28:29], off nt
	global_load_dword v59, v[30:31], off nt
	global_load_dword v65, v[32:33], off nt
	global_load_dword v66, v[34:35], off nt
	global_load_dword v67, v[36:37], off nt
	global_load_dword v68, v[38:39], off nt
	global_load_dword v69, v[40:41], off nt
	global_load_dword v70, v[42:43], off nt
	global_load_dword v71, v[44:45], off nt
	global_load_dword v72, v[46:47], off nt
	global_load_dword v73, v[48:49], off nt
	global_load_dword v74, v[50:51], off nt
	global_load_dword v75, v[52:53], off nt
	global_load_dword v24, v[54:55], off nt
	s_add_i32 s17, s17, 32
	v_add_u32_e32 v196, s17, v22
	v_ashrrev_i32_e32 v197, 31, v196
	v_add_u32_e32 v198, 2, v196
	v_add_u32_e32 v200, 4, v196
	v_add_u32_e32 v202, 6, v196
	v_add_u32_e32 v204, 8, v196
	v_add_u32_e32 v206, 10, v196
	v_add_u32_e32 v208, 12, v196
	v_add_u32_e32 v210, 14, v196
	v_add_u32_e32 v212, 16, v196
	v_add_u32_e32 v214, 18, v196
	v_add_u32_e32 v216, 20, v196
	v_add_u32_e32 v218, 22, v196
	v_add_u32_e32 v220, 24, v196
	v_add_u32_e32 v222, 26, v196
	v_add_u32_e32 v224, 28, v196
	v_add_u32_e32 v226, 30, v196
	v_lshlrev_b64 v[196:197], 12, v[196:197]
	v_ashrrev_i32_e32 v199, 31, v198
	v_ashrrev_i32_e32 v201, 31, v200
	v_ashrrev_i32_e32 v203, 31, v202
	v_ashrrev_i32_e32 v205, 31, v204
	v_ashrrev_i32_e32 v207, 31, v206
	v_ashrrev_i32_e32 v209, 31, v208
	v_ashrrev_i32_e32 v211, 31, v210
	v_ashrrev_i32_e32 v213, 31, v212
	v_ashrrev_i32_e32 v215, 31, v214
	v_ashrrev_i32_e32 v217, 31, v216
	v_ashrrev_i32_e32 v219, 31, v218
	v_ashrrev_i32_e32 v221, 31, v220
	v_ashrrev_i32_e32 v223, 31, v222
	v_ashrrev_i32_e32 v225, 31, v224
	v_ashrrev_i32_e32 v227, 31, v226
	v_lshl_add_u64 v[196:197], v[20:21], 0, v[196:197]
	v_lshlrev_b64 v[198:199], 12, v[198:199]
	v_lshlrev_b64 v[200:201], 12, v[200:201]
	v_lshlrev_b64 v[202:203], 12, v[202:203]
	v_lshlrev_b64 v[204:205], 12, v[204:205]
	v_lshlrev_b64 v[206:207], 12, v[206:207]
	v_lshlrev_b64 v[208:209], 12, v[208:209]
	v_lshlrev_b64 v[210:211], 12, v[210:211]
	v_lshlrev_b64 v[212:213], 12, v[212:213]
	v_lshlrev_b64 v[214:215], 12, v[214:215]
	v_lshlrev_b64 v[216:217], 12, v[216:217]
	v_lshlrev_b64 v[218:219], 12, v[218:219]
	v_lshlrev_b64 v[220:221], 12, v[220:221]
	v_lshlrev_b64 v[222:223], 12, v[222:223]
	v_lshlrev_b64 v[224:225], 12, v[224:225]
	v_lshlrev_b64 v[226:227], 12, v[226:227]
	v_lshl_add_u64 v[198:199], v[20:21], 0, v[198:199]
	v_lshl_add_u64 v[200:201], v[20:21], 0, v[200:201]
	v_lshl_add_u64 v[202:203], v[20:21], 0, v[202:203]
	v_lshl_add_u64 v[204:205], v[20:21], 0, v[204:205]
	v_lshl_add_u64 v[206:207], v[20:21], 0, v[206:207]
	v_lshl_add_u64 v[208:209], v[20:21], 0, v[208:209]
	v_lshl_add_u64 v[210:211], v[20:21], 0, v[210:211]
	v_lshl_add_u64 v[212:213], v[20:21], 0, v[212:213]
	v_lshl_add_u64 v[214:215], v[20:21], 0, v[214:215]
	v_lshl_add_u64 v[216:217], v[20:21], 0, v[216:217]
	v_lshl_add_u64 v[218:219], v[20:21], 0, v[218:219]
	v_lshl_add_u64 v[220:221], v[20:21], 0, v[220:221]
	v_lshl_add_u64 v[222:223], v[20:21], 0, v[222:223]
	v_lshl_add_u64 v[224:225], v[20:21], 0, v[224:225]
	v_lshl_add_u64 v[226:227], v[20:21], 0, v[226:227]
	global_load_dword v228, v[196:197], off nt
	global_load_dword v229, v[198:199], off nt
	global_load_dword v230, v[200:201], off nt
	global_load_dword v231, v[202:203], off nt
	global_load_dword v165, v[204:205], off nt
	global_load_dword v166, v[206:207], off nt
	global_load_dword v167, v[208:209], off nt
	global_load_dword v168, v[210:211], off nt
	global_load_dword v169, v[212:213], off nt
	global_load_dword v170, v[214:215], off nt
	global_load_dword v171, v[216:217], off nt
	global_load_dword v172, v[218:219], off nt
	global_load_dword v173, v[220:221], off nt
	global_load_dword v174, v[222:223], off nt
	global_load_dword v175, v[224:225], off nt
	global_load_dword v196, v[226:227], off nt
	v_add_u32_e32 v25, 0x400, v23
	v_add_u32_e32 v26, 0x800, v23
	v_add_u32_e32 v27, 0xc00, v23
	s_waitcnt vmcnt(30)
; __device__ __forceinline__ unsigned pk2h(float lo, float hi) { const f32x2p_t v = {lo, hi}; const f16x2_t hv = __builtin_convertvector(v, f16x2_t); return __builtin_bit_cast(unsigned, hv); }
; #define LAS __attribute__((address_space(3)))
; __device__ __forceinline__ unsigned pk2(float lo, float hi) { f32x2_t v = {lo, hi}; bf16x2_t b = __builtin_convertvector(v, bf16x2_t); return __builtin_bit_cast(unsigned, b); }
; __device__ __forceinline__ void conv_item(const float* W, int K, int N, bf16* WT, const float* gain, int mapmode, bool f16, LAS float* scr, int item, int lane) {
;     ...
;     for (int i = 0; i < 32; ++i) { const int kk = 2 * i + (lane >> 5); float v = __builtin_nontemporal_load(W + (size_t)(k0 + kk) * N + n0 + (lane & 31)); if (gain) v *= gain[k0 + kk]; scr[kk * 33 + (lane & 31)] = v; }
;     asm volatile("s_waitcnt lgkmcnt(0)" ::: "memory");
;     const int c = lane & 7;
; #pragma unroll
;     for (int j = 0; j < 4; ++j) { const int nl = (lane >> 3) + 8 * j; int n = n0 + nl;
;         if (mapmode == 1) { n = n < DFF ? (n / 128) * 256 + (n % 128) : ((n - DFF) / 128) * 256 + 128 + ((n - DFF) % 128); }
;         const LAS float* s = scr + (8 * c) * 33 + nl;
;         u32x4 o; if (f16) { o.x = pg8::pk2h(s[0 * 33], s[1 * 33]); o.y = pg8::pk2h(s[2 * 33], s[3 * 33]); o.z = pg8::pk2h(s[4 * 33], s[5 * 33]); o.w = pg8::pk2h(s[6 * 33], s[7 * 33]); }
;         else { o.x = pk2(s[0 * 33], s[1 * 33]); o.y = pk2(s[2 * 33], s[3 * 33]); o.z = pk2(s[4 * 33], s[5 * 33]); o.w = pk2(s[6 * 33], s[7 * 33]); }
;         *(u32x4*)(WT + (size_t)n * K + k0 + 8 * c) = o; }
;     asm volatile("s_waitcnt lgkmcnt(0)" ::: "memory");
	ds_write2_b32 v23, v56, v57 offset1:66
	s_waitcnt vmcnt(28)
	ds_write2_b32 v23, v58, v59 offset0:132 offset1:198
	s_waitcnt vmcnt(26)
	ds_write2_b32 v25, v65, v66 offset0:8 offset1:74
	s_waitcnt vmcnt(24)
	ds_write2_b32 v25, v67, v68 offset0:140 offset1:206
	s_waitcnt vmcnt(22)
	ds_write2_b32 v26, v69, v70 offset0:16 offset1:82
	s_waitcnt vmcnt(20)
	ds_write2_b32 v26, v71, v72 offset0:148 offset1:214
	s_waitcnt vmcnt(18)
	ds_write2_b32 v27, v73, v74 offset0:24 offset1:90
	s_waitcnt vmcnt(16)
	ds_write2_b32 v27, v75, v24 offset0:156 offset1:222
	v_add_u32_e32 v23, 0x1080, v23
	v_add_u32_e32 v25, 0x400, v23
	v_add_u32_e32 v26, 0x800, v23
	v_add_u32_e32 v27, 0xc00, v23
	s_waitcnt vmcnt(14)
	ds_write2_b32 v23, v228, v229 offset1:66
	s_waitcnt vmcnt(12)
	ds_write2_b32 v23, v230, v231 offset0:132 offset1:198
	s_waitcnt vmcnt(10)
	ds_write2_b32 v25, v165, v166 offset0:8 offset1:74
	s_waitcnt vmcnt(8)
	ds_write2_b32 v25, v167, v168 offset0:140 offset1:206
	s_waitcnt vmcnt(6)
	ds_write2_b32 v26, v169, v170 offset0:16 offset1:82
	s_waitcnt vmcnt(4)
	ds_write2_b32 v26, v171, v172 offset0:148 offset1:214
	s_waitcnt vmcnt(2)
	ds_write2_b32 v27, v173, v174 offset0:24 offset1:90
	s_waitcnt vmcnt(0)
	ds_write2_b32 v27, v175, v196 offset0:156 offset1:222
	v_add_u32_e32 v23, 0x1080, v23
	s_add_i32 s17, s17, 32
	s_waitcnt lgkmcnt(0)
	ds_read2_b32 v[26:27], v60 offset0:33 offset1:41
	ds_read2_b32 v[28:29], v60 offset1:8
	ds_read2_b32 v[30:31], v60 offset0:66 offset1:74
	ds_read2_b32 v[32:33], v60 offset0:99 offset1:107
	ds_read2_b32 v[34:35], v60 offset0:132 offset1:140
	ds_read2_b32 v[36:37], v60 offset0:165 offset1:173
	ds_read2_b32 v[38:39], v60 offset0:198 offset1:206
	ds_read2_b32 v[40:41], v60 offset0:231 offset1:239
	v_or_b32_e32 v42, s16, v3
	s_ashr_i32 s27, s26, 31
	v_ashrrev_i32_e32 v43, 31, v42
	v_lshl_add_u64 v[24:25], s[26:27], 1, v[18:19]
	v_lshlrev_b64 v[42:43], 11, v[42:43]
	s_waitcnt lgkmcnt(6)
	v_cvt_pk_bf16_f32 v20, v28, v26
	s_waitcnt lgkmcnt(4)
	v_cvt_pk_bf16_f32 v21, v30, v32
	s_waitcnt lgkmcnt(2)
	v_cvt_pk_bf16_f32 v22, v34, v36
	s_waitcnt lgkmcnt(0)
	v_cvt_pk_bf16_f32 v23, v38, v40
	v_lshl_add_u64 v[42:43], v[24:25], 0, v[42:43]
	v_or_b32_e32 v26, s16, v61
	global_store_dwordx4 v[42:43], v[20:23], off
	v_or_b32_e32 v42, s16, v62
	v_ashrrev_i32_e32 v43, 31, v42
	v_cvt_pk_bf16_f32 v20, v29, v27
	v_ashrrev_i32_e32 v27, 31, v26
	v_lshlrev_b64 v[26:27], 11, v[26:27]
	v_cvt_pk_bf16_f32 v21, v31, v33
	v_cvt_pk_bf16_f32 v22, v35, v37
	v_cvt_pk_bf16_f32 v23, v39, v41
	v_lshl_add_u64 v[26:27], v[24:25], 0, v[26:27]
	global_store_dwordx4 v[26:27], v[20:23], off
	ds_read2_b32 v[26:27], v60 offset0:49 offset1:57
	ds_read2_b32 v[28:29], v60 offset0:16 offset1:24
	ds_read2_b32 v[30:31], v60 offset0:82 offset1:90
	ds_read2_b32 v[32:33], v60 offset0:115 offset1:123
	ds_read2_b32 v[34:35], v60 offset0:148 offset1:156
	ds_read2_b32 v[36:37], v60 offset0:181 offset1:189
	ds_read2_b32 v[38:39], v60 offset0:214 offset1:222
	ds_read2_b32 v[40:41], v60 offset0:247 offset1:255
	v_lshlrev_b64 v[42:43], 11, v[42:43]
	s_waitcnt lgkmcnt(6)
	v_cvt_pk_bf16_f32 v20, v28, v26
	s_waitcnt lgkmcnt(4)
	v_cvt_pk_bf16_f32 v21, v30, v32
	s_waitcnt lgkmcnt(2)
	v_cvt_pk_bf16_f32 v22, v34, v36
	s_waitcnt lgkmcnt(0)
	v_cvt_pk_bf16_f32 v23, v38, v40
	v_lshl_add_u64 v[42:43], v[24:25], 0, v[42:43]
	v_or_b32_e32 v26, s16, v63
	global_store_dwordx4 v[42:43], v[20:23], off
	s_add_i32 s29, s29, s24
	s_cmpk_gt_i32 s29, 0x1ff
	v_cvt_pk_bf16_f32 v20, v29, v27
	v_ashrrev_i32_e32 v27, 31, v26
	v_lshlrev_b64 v[26:27], 11, v[26:27]
	v_cvt_pk_bf16_f32 v21, v31, v33
	v_cvt_pk_bf16_f32 v22, v35, v37
	v_cvt_pk_bf16_f32 v23, v39, v41
	v_lshl_add_u64 v[24:25], v[24:25], 0, v[26:27]
	global_store_dwordx4 v[24:25], v[20:23], off
	s_waitcnt lgkmcnt(0)
	s_cbranch_scc0 .LBB0_45

; __device__ __forceinline__ void conv_item(const float* W, int K, int N, bf16* WT, const float* gain, int mapmode, bool f16, LAS float* scr, int item, int lane) {
;     ...
; #pragma unroll 16
;     for (int i = 0; i < 32; ++i) { const int kk = 2 * i + (lane >> 5); float v = __builtin_nontemporal_load(W + (size_t)(k0 + kk) * N + n0 + (lane & 31)); if (gain) v *= gain[k0 + kk]; scr[kk * 33 + (lane & 31)] = v; }
.LBB0_56:
	v_add_u32_e32 v24, s5, v22
	v_ashrrev_i32_e32 v25, 31, v24
	v_add_u32_e32 v26, 2, v24
	v_add_u32_e32 v28, 4, v24
	v_add_u32_e32 v30, 6, v24
	v_add_u32_e32 v32, 8, v24
	v_add_u32_e32 v34, 10, v24
	v_add_u32_e32 v36, 12, v24
	v_add_u32_e32 v38, 14, v24
	v_add_u32_e32 v40, 16, v24
	v_add_u32_e32 v42, 18, v24
	v_add_u32_e32 v44, 20, v24
	v_add_u32_e32 v46, 22, v24
	v_add_u32_e32 v48, 24, v24
	v_add_u32_e32 v50, 26, v24
	v_add_u32_e32 v52, 28, v24
	v_add_u32_e32 v54, 30, v24
	v_lshlrev_b64 v[24:25], 12, v[24:25]
	v_ashrrev_i32_e32 v27, 31, v26
	v_ashrrev_i32_e32 v29, 31, v28
	v_ashrrev_i32_e32 v31, 31, v30
	v_ashrrev_i32_e32 v33, 31, v32
	v_ashrrev_i32_e32 v35, 31, v34
	v_ashrrev_i32_e32 v37, 31, v36
	v_ashrrev_i32_e32 v39, 31, v38
	v_ashrrev_i32_e32 v41, 31, v40
	v_ashrrev_i32_e32 v43, 31, v42
	v_ashrrev_i32_e32 v45, 31, v44
	v_ashrrev_i32_e32 v47, 31, v46
	v_ashrrev_i32_e32 v49, 31, v48
	v_ashrrev_i32_e32 v51, 31, v50
	v_ashrrev_i32_e32 v53, 31, v52
	v_ashrrev_i32_e32 v55, 31, v54
	v_lshl_add_u64 v[24:25], v[20:21], 0, v[24:25]
	v_lshlrev_b64 v[26:27], 12, v[26:27]
	v_lshlrev_b64 v[28:29], 12, v[28:29]
	v_lshlrev_b64 v[30:31], 12, v[30:31]
	v_lshlrev_b64 v[32:33], 12, v[32:33]
	v_lshlrev_b64 v[34:35], 12, v[34:35]
	v_lshlrev_b64 v[36:37], 12, v[36:37]
	v_lshlrev_b64 v[38:39], 12, v[38:39]
	v_lshlrev_b64 v[40:41], 12, v[40:41]
	v_lshlrev_b64 v[42:43], 12, v[42:43]
	v_lshlrev_b64 v[44:45], 12, v[44:45]
	v_lshlrev_b64 v[46:47], 12, v[46:47]
	v_lshlrev_b64 v[48:49], 12, v[48:49]
	v_lshlrev_b64 v[50:51], 12, v[50:51]
	v_lshlrev_b64 v[52:53], 12, v[52:53]
	v_lshlrev_b64 v[54:55], 12, v[54:55]
	v_lshl_add_u64 v[26:27], v[20:21], 0, v[26:27]
	v_lshl_add_u64 v[28:29], v[20:21], 0, v[28:29]
	v_lshl_add_u64 v[30:31], v[20:21], 0, v[30:31]
	v_lshl_add_u64 v[32:33], v[20:21], 0, v[32:33]
	v_lshl_add_u64 v[34:35], v[20:21], 0, v[34:35]
	v_lshl_add_u64 v[36:37], v[20:21], 0, v[36:37]
	v_lshl_add_u64 v[38:39], v[20:21], 0, v[38:39]
	v_lshl_add_u64 v[40:41], v[20:21], 0, v[40:41]
	v_lshl_add_u64 v[42:43], v[20:21], 0, v[42:43]
	v_lshl_add_u64 v[44:45], v[20:21], 0, v[44:45]
	v_lshl_add_u64 v[46:47], v[20:21], 0, v[46:47]
	v_lshl_add_u64 v[48:49], v[20:21], 0, v[48:49]
	v_lshl_add_u64 v[50:51], v[20:21], 0, v[50:51]
	v_lshl_add_u64 v[52:53], v[20:21], 0, v[52:53]
	v_lshl_add_u64 v[54:55], v[20:21], 0, v[54:55]
	global_load_dword v56, v[24:25], off nt
	global_load_dword v57, v[26:27], off nt
	global_load_dword v58, v[28:29], off nt
	global_load_dword v59, v[30:31], off nt
	global_load_dword v65, v[32:33], off nt
	global_load_dword v66, v[34:35], off nt
	global_load_dword v67, v[36:37], off nt
	global_load_dword v68, v[38:39], off nt
	global_load_dword v69, v[40:41], off nt
	global_load_dword v70, v[42:43], off nt
	global_load_dword v71, v[44:45], off nt
	global_load_dword v72, v[46:47], off nt
	global_load_dword v73, v[48:49], off nt
	global_load_dword v74, v[50:51], off nt
	global_load_dword v75, v[52:53], off nt
	global_load_dword v24, v[54:55], off nt
	s_add_i32 s5, s5, 32
	v_add_u32_e32 v196, s5, v22
	v_ashrrev_i32_e32 v197, 31, v196
	v_add_u32_e32 v198, 2, v196
	v_add_u32_e32 v200, 4, v196
	v_add_u32_e32 v202, 6, v196
	v_add_u32_e32 v204, 8, v196
	v_add_u32_e32 v206, 10, v196
	v_add_u32_e32 v208, 12, v196
	v_add_u32_e32 v210, 14, v196
	v_add_u32_e32 v212, 16, v196
	v_add_u32_e32 v214, 18, v196
	v_add_u32_e32 v216, 20, v196
	v_add_u32_e32 v218, 22, v196
	v_add_u32_e32 v220, 24, v196
	v_add_u32_e32 v222, 26, v196
	v_add_u32_e32 v224, 28, v196
	v_add_u32_e32 v226, 30, v196
	v_lshlrev_b64 v[196:197], 12, v[196:197]
	v_ashrrev_i32_e32 v199, 31, v198
	v_ashrrev_i32_e32 v201, 31, v200
	v_ashrrev_i32_e32 v203, 31, v202
	v_ashrrev_i32_e32 v205, 31, v204
	v_ashrrev_i32_e32 v207, 31, v206
	v_ashrrev_i32_e32 v209, 31, v208
	v_ashrrev_i32_e32 v211, 31, v210
	v_ashrrev_i32_e32 v213, 31, v212
	v_ashrrev_i32_e32 v215, 31, v214
	v_ashrrev_i32_e32 v217, 31, v216
	v_ashrrev_i32_e32 v219, 31, v218
	v_ashrrev_i32_e32 v221, 31, v220
	v_ashrrev_i32_e32 v223, 31, v222
	v_ashrrev_i32_e32 v225, 31, v224
	v_ashrrev_i32_e32 v227, 31, v226
	v_lshl_add_u64 v[196:197], v[20:21], 0, v[196:197]
	v_lshlrev_b64 v[198:199], 12, v[198:199]
	v_lshlrev_b64 v[200:201], 12, v[200:201]
	v_lshlrev_b64 v[202:203], 12, v[202:203]
	v_lshlrev_b64 v[204:205], 12, v[204:205]
	v_lshlrev_b64 v[206:207], 12, v[206:207]
	v_lshlrev_b64 v[208:209], 12, v[208:209]
	v_lshlrev_b64 v[210:211], 12, v[210:211]
	v_lshlrev_b64 v[212:213], 12, v[212:213]
	v_lshlrev_b64 v[214:215], 12, v[214:215]
	v_lshlrev_b64 v[216:217], 12, v[216:217]
	v_lshlrev_b64 v[218:219], 12, v[218:219]
	v_lshlrev_b64 v[220:221], 12, v[220:221]
	v_lshlrev_b64 v[222:223], 12, v[222:223]
	v_lshlrev_b64 v[224:225], 12, v[224:225]
	v_lshlrev_b64 v[226:227], 12, v[226:227]
	v_lshl_add_u64 v[198:199], v[20:21], 0, v[198:199]
	v_lshl_add_u64 v[200:201], v[20:21], 0, v[200:201]
	v_lshl_add_u64 v[202:203], v[20:21], 0, v[202:203]
	v_lshl_add_u64 v[204:205], v[20:21], 0, v[204:205]
	v_lshl_add_u64 v[206:207], v[20:21], 0, v[206:207]
	v_lshl_add_u64 v[208:209], v[20:21], 0, v[208:209]
	v_lshl_add_u64 v[210:211], v[20:21], 0, v[210:211]
	v_lshl_add_u64 v[212:213], v[20:21], 0, v[212:213]
	v_lshl_add_u64 v[214:215], v[20:21], 0, v[214:215]
	v_lshl_add_u64 v[216:217], v[20:21], 0, v[216:217]
	v_lshl_add_u64 v[218:219], v[20:21], 0, v[218:219]
	v_lshl_add_u64 v[220:221], v[20:21], 0, v[220:221]
	v_lshl_add_u64 v[222:223], v[20:21], 0, v[222:223]
	v_lshl_add_u64 v[224:225], v[20:21], 0, v[224:225]
	v_lshl_add_u64 v[226:227], v[20:21], 0, v[226:227]
	global_load_dword v228, v[196:197], off nt
	global_load_dword v229, v[198:199], off nt
	global_load_dword v230, v[200:201], off nt
	global_load_dword v231, v[202:203], off nt
	global_load_dword v165, v[204:205], off nt
	global_load_dword v166, v[206:207], off nt
	global_load_dword v167, v[208:209], off nt
	global_load_dword v168, v[210:211], off nt
	global_load_dword v169, v[212:213], off nt
	global_load_dword v170, v[214:215], off nt
	global_load_dword v171, v[216:217], off nt
	global_load_dword v172, v[218:219], off nt
	global_load_dword v173, v[220:221], off nt
	global_load_dword v174, v[222:223], off nt
	global_load_dword v175, v[224:225], off nt
	global_load_dword v196, v[226:227], off nt
	v_add_u32_e32 v25, 0x400, v23
	v_add_u32_e32 v26, 0x800, v23
	v_add_u32_e32 v27, 0xc00, v23
	s_waitcnt vmcnt(30)
; __device__ __forceinline__ unsigned pk2h(float lo, float hi) { const f32x2p_t v = {lo, hi}; const f16x2_t hv = __builtin_convertvector(v, f16x2_t); return __builtin_bit_cast(unsigned, hv); }
; #define LAS __attribute__((address_space(3)))
; __device__ __forceinline__ unsigned pk2(float lo, float hi) { f32x2_t v = {lo, hi}; bf16x2_t b = __builtin_convertvector(v, bf16x2_t); return __builtin_bit_cast(unsigned, b); }
; __device__ __forceinline__ void conv_item(const float* W, int K, int N, bf16* WT, const float* gain, int mapmode, bool f16, LAS float* scr, int item, int lane) {
;     ...
;     for (int i = 0; i < 32; ++i) { const int kk = 2 * i + (lane >> 5); float v = __builtin_nontemporal_load(W + (size_t)(k0 + kk) * N + n0 + (lane & 31)); if (gain) v *= gain[k0 + kk]; scr[kk * 33 + (lane & 31)] = v; }
;     asm volatile("s_waitcnt lgkmcnt(0)" ::: "memory");
;     const int c = lane & 7;
; #pragma unroll
;     for (int j = 0; j < 4; ++j) { const int nl = (lane >> 3) + 8 * j; int n = n0 + nl;
;         if (mapmode == 1) { n = n < DFF ? (n / 128) * 256 + (n % 128) : ((n - DFF) / 128) * 256 + 128 + ((n - DFF) % 128); }
;         const LAS float* s = scr + (8 * c) * 33 + nl;
;         u32x4 o; if (f16) { o.x = pg8::pk2h(s[0 * 33], s[1 * 33]); o.y = pg8::pk2h(s[2 * 33], s[3 * 33]); o.z = pg8::pk2h(s[4 * 33], s[5 * 33]); o.w = pg8::pk2h(s[6 * 33], s[7 * 33]); }
;         else { o.x = pk2(s[0 * 33], s[1 * 33]); o.y = pk2(s[2 * 33], s[3 * 33]); o.z = pk2(s[4 * 33], s[5 * 33]); o.w = pk2(s[6 * 33], s[7 * 33]); }
;         *(u32x4*)(WT + (size_t)n * K + k0 + 8 * c) = o; }
;     asm volatile("s_waitcnt lgkmcnt(0)" ::: "memory");
	ds_write2_b32 v23, v56, v57 offset1:66
	s_waitcnt vmcnt(28)
	ds_write2_b32 v23, v58, v59 offset0:132 offset1:198
	s_waitcnt vmcnt(26)
	ds_write2_b32 v25, v65, v66 offset0:8 offset1:74
	s_waitcnt vmcnt(24)
	ds_write2_b32 v25, v67, v68 offset0:140 offset1:206
	s_waitcnt vmcnt(22)
	ds_write2_b32 v26, v69, v70 offset0:16 offset1:82
	s_waitcnt vmcnt(20)
	ds_write2_b32 v26, v71, v72 offset0:148 offset1:214
	s_waitcnt vmcnt(18)
	ds_write2_b32 v27, v73, v74 offset0:24 offset1:90
	s_waitcnt vmcnt(16)
	ds_write2_b32 v27, v75, v24 offset0:156 offset1:222
	v_add_u32_e32 v23, 0x1080, v23
	v_add_u32_e32 v25, 0x400, v23
	v_add_u32_e32 v26, 0x800, v23
	v_add_u32_e32 v27, 0xc00, v23
	s_waitcnt vmcnt(14)
	ds_write2_b32 v23, v228, v229 offset1:66
	s_waitcnt vmcnt(12)
	ds_write2_b32 v23, v230, v231 offset0:132 offset1:198
	s_waitcnt vmcnt(10)
	ds_write2_b32 v25, v165, v166 offset0:8 offset1:74
	s_waitcnt vmcnt(8)
	ds_write2_b32 v25, v167, v168 offset0:140 offset1:206
	s_waitcnt vmcnt(6)
	ds_write2_b32 v26, v169, v170 offset0:16 offset1:82
	s_waitcnt vmcnt(4)
	ds_write2_b32 v26, v171, v172 offset0:148 offset1:214
	s_waitcnt vmcnt(2)
	ds_write2_b32 v27, v173, v174 offset0:24 offset1:90
	s_waitcnt vmcnt(0)
	ds_write2_b32 v27, v175, v196 offset0:156 offset1:222
	v_add_u32_e32 v23, 0x1080, v23
	s_add_i32 s5, s5, 32
	s_waitcnt lgkmcnt(0)
	ds_read2_b32 v[26:27], v60 offset0:33 offset1:41
	ds_read2_b32 v[28:29], v60 offset1:8
	ds_read2_b32 v[30:31], v60 offset0:66 offset1:74
	ds_read2_b32 v[32:33], v60 offset0:99 offset1:107
	ds_read2_b32 v[34:35], v60 offset0:132 offset1:140
	ds_read2_b32 v[36:37], v60 offset0:165 offset1:173
	ds_read2_b32 v[38:39], v60 offset0:198 offset1:206
	ds_read2_b32 v[40:41], v60 offset0:231 offset1:239
	v_or_b32_e32 v42, s4, v3
	s_ashr_i32 s13, s12, 31
	v_ashrrev_i32_e32 v43, 31, v42
	v_lshl_add_u64 v[24:25], s[12:13], 1, v[18:19]
	v_lshlrev_b64 v[42:43], 11, v[42:43]
	s_waitcnt lgkmcnt(6)
	v_cvt_pk_bf16_f32 v20, v28, v26
	s_waitcnt lgkmcnt(4)
	v_cvt_pk_bf16_f32 v21, v30, v32
	s_waitcnt lgkmcnt(2)
	v_cvt_pk_bf16_f32 v22, v34, v36
	s_waitcnt lgkmcnt(0)
	v_cvt_pk_bf16_f32 v23, v38, v40
	v_lshl_add_u64 v[42:43], v[24:25], 0, v[42:43]
	v_or_b32_e32 v26, s4, v61
	global_store_dwordx4 v[42:43], v[20:23], off
	v_or_b32_e32 v42, s4, v62
	v_ashrrev_i32_e32 v43, 31, v42
	v_cvt_pk_bf16_f32 v20, v29, v27
	v_ashrrev_i32_e32 v27, 31, v26
	v_lshlrev_b64 v[26:27], 11, v[26:27]
	v_cvt_pk_bf16_f32 v21, v31, v33
	v_cvt_pk_bf16_f32 v22, v35, v37
	v_cvt_pk_bf16_f32 v23, v39, v41
	v_lshl_add_u64 v[26:27], v[24:25], 0, v[26:27]
	global_store_dwordx4 v[26:27], v[20:23], off
	ds_read2_b32 v[26:27], v60 offset0:49 offset1:57
	ds_read2_b32 v[28:29], v60 offset0:16 offset1:24
	ds_read2_b32 v[30:31], v60 offset0:82 offset1:90
	ds_read2_b32 v[32:33], v60 offset0:115 offset1:123
	ds_read2_b32 v[34:35], v60 offset0:148 offset1:156
	ds_read2_b32 v[36:37], v60 offset0:181 offset1:189
	ds_read2_b32 v[38:39], v60 offset0:214 offset1:222
	ds_read2_b32 v[40:41], v60 offset0:247 offset1:255
	v_lshlrev_b64 v[42:43], 11, v[42:43]
	s_waitcnt lgkmcnt(6)
	v_cvt_pk_bf16_f32 v20, v28, v26
	s_waitcnt lgkmcnt(4)
	v_cvt_pk_bf16_f32 v21, v30, v32
	s_waitcnt lgkmcnt(2)
	v_cvt_pk_bf16_f32 v22, v34, v36
	s_waitcnt lgkmcnt(0)
	v_cvt_pk_bf16_f32 v23, v38, v40
	v_lshl_add_u64 v[42:43], v[24:25], 0, v[42:43]
	v_or_b32_e32 v26, s4, v63
	global_store_dwordx4 v[42:43], v[20:23], off
	s_add_i32 s16, s16, s24
	s_cmpk_gt_i32 s16, 0x1ff
	v_cvt_pk_bf16_f32 v20, v29, v27
	v_ashrrev_i32_e32 v27, 31, v26
	v_lshlrev_b64 v[26:27], 11, v[26:27]
	v_cvt_pk_bf16_f32 v21, v31, v33
	v_cvt_pk_bf16_f32 v22, v35, v37
	v_cvt_pk_bf16_f32 v23, v39, v41
	v_lshl_add_u64 v[24:25], v[24:25], 0, v[26:27]
	global_store_dwordx4 v[24:25], v[20:23], off
	s_waitcnt lgkmcnt(0)
	s_cbranch_scc0 .LBB0_55
	s_branch .LBB0_5

; __device__ __forceinline__ void conv_item(const float* W, int K, int N, bf16* WT, const float* gain, int mapmode, bool f16, LAS float* scr, int item, int lane) {
;     ...
; #pragma unroll 16
;     for (int i = 0; i < 32; ++i) { const int kk = 2 * i + (lane >> 5); float v = __builtin_nontemporal_load(W + (size_t)(k0 + kk) * N + n0 + (lane & 31)); if (gain) v *= gain[k0 + kk]; scr[kk * 33 + (lane & 31)] = v; }
.LBB0_137:
	v_add_u32_e32 v26, s5, v24
	v_ashrrev_i32_e32 v27, 31, v26
	v_add_u32_e32 v28, 2, v26
	v_add_u32_e32 v30, 4, v26
	v_add_u32_e32 v32, 6, v26
	v_add_u32_e32 v34, 8, v26
	v_add_u32_e32 v36, 10, v26
	v_add_u32_e32 v38, 12, v26
	v_add_u32_e32 v40, 14, v26
	v_add_u32_e32 v42, 16, v26
	v_add_u32_e32 v44, 18, v26
	v_add_u32_e32 v46, 20, v26
	v_add_u32_e32 v48, 22, v26
	v_add_u32_e32 v50, 24, v26
	v_add_u32_e32 v52, 26, v26
	v_add_u32_e32 v54, 28, v26
	v_add_u32_e32 v56, 30, v26
	v_lshlrev_b64 v[26:27], 12, v[26:27]
	v_ashrrev_i32_e32 v29, 31, v28
	v_ashrrev_i32_e32 v31, 31, v30
	v_ashrrev_i32_e32 v33, 31, v32
	v_ashrrev_i32_e32 v35, 31, v34
	v_ashrrev_i32_e32 v37, 31, v36
	v_ashrrev_i32_e32 v39, 31, v38
	v_ashrrev_i32_e32 v41, 31, v40
	v_ashrrev_i32_e32 v43, 31, v42
	v_ashrrev_i32_e32 v45, 31, v44
	v_ashrrev_i32_e32 v47, 31, v46
	v_ashrrev_i32_e32 v49, 31, v48
	v_ashrrev_i32_e32 v51, 31, v50
	v_ashrrev_i32_e32 v53, 31, v52
	v_ashrrev_i32_e32 v55, 31, v54
	v_ashrrev_i32_e32 v57, 31, v56
	v_lshl_add_u64 v[26:27], v[22:23], 0, v[26:27]
	v_lshlrev_b64 v[28:29], 12, v[28:29]
	v_lshlrev_b64 v[30:31], 12, v[30:31]
	v_lshlrev_b64 v[32:33], 12, v[32:33]
	v_lshlrev_b64 v[34:35], 12, v[34:35]
	v_lshlrev_b64 v[36:37], 12, v[36:37]
	v_lshlrev_b64 v[38:39], 12, v[38:39]
	v_lshlrev_b64 v[40:41], 12, v[40:41]
	v_lshlrev_b64 v[42:43], 12, v[42:43]
	v_lshlrev_b64 v[44:45], 12, v[44:45]
	v_lshlrev_b64 v[46:47], 12, v[46:47]
	v_lshlrev_b64 v[48:49], 12, v[48:49]
	v_lshlrev_b64 v[50:51], 12, v[50:51]
	v_lshlrev_b64 v[52:53], 12, v[52:53]
	v_lshlrev_b64 v[54:55], 12, v[54:55]
	v_lshlrev_b64 v[56:57], 12, v[56:57]
	v_lshl_add_u64 v[28:29], v[22:23], 0, v[28:29]
	v_lshl_add_u64 v[30:31], v[22:23], 0, v[30:31]
	v_lshl_add_u64 v[32:33], v[22:23], 0, v[32:33]
	v_lshl_add_u64 v[34:35], v[22:23], 0, v[34:35]
	v_lshl_add_u64 v[36:37], v[22:23], 0, v[36:37]
	v_lshl_add_u64 v[38:39], v[22:23], 0, v[38:39]
	v_lshl_add_u64 v[40:41], v[22:23], 0, v[40:41]
	v_lshl_add_u64 v[42:43], v[22:23], 0, v[42:43]
	v_lshl_add_u64 v[44:45], v[22:23], 0, v[44:45]
	v_lshl_add_u64 v[46:47], v[22:23], 0, v[46:47]
	v_lshl_add_u64 v[48:49], v[22:23], 0, v[48:49]
	v_lshl_add_u64 v[50:51], v[22:23], 0, v[50:51]
	v_lshl_add_u64 v[52:53], v[22:23], 0, v[52:53]
	v_lshl_add_u64 v[54:55], v[22:23], 0, v[54:55]
	v_lshl_add_u64 v[56:57], v[22:23], 0, v[56:57]
	global_load_dword v58, v[26:27], off nt
	global_load_dword v59, v[28:29], off nt
	global_load_dword v83, v[30:31], off nt
	global_load_dword v84, v[32:33], off nt
	global_load_dword v85, v[34:35], off nt
	global_load_dword v86, v[36:37], off nt
	global_load_dword v87, v[38:39], off nt
	global_load_dword v88, v[40:41], off nt
	global_load_dword v89, v[42:43], off nt
	global_load_dword v90, v[44:45], off nt
	global_load_dword v91, v[46:47], off nt
	global_load_dword v92, v[48:49], off nt
	global_load_dword v93, v[50:51], off nt
	global_load_dword v94, v[52:53], off nt
	global_load_dword v95, v[54:55], off nt
	global_load_dword v26, v[56:57], off nt
	s_add_i32 s5, s5, 32
	v_add_u32_e32 v196, s5, v24
	v_ashrrev_i32_e32 v197, 31, v196
	v_add_u32_e32 v198, 2, v196
	v_add_u32_e32 v200, 4, v196
	v_add_u32_e32 v202, 6, v196
	v_add_u32_e32 v204, 8, v196
	v_add_u32_e32 v206, 10, v196
	v_add_u32_e32 v208, 12, v196
	v_add_u32_e32 v210, 14, v196
	v_add_u32_e32 v212, 16, v196
	v_add_u32_e32 v214, 18, v196
	v_add_u32_e32 v216, 20, v196
	v_add_u32_e32 v218, 22, v196
	v_add_u32_e32 v220, 24, v196
	v_add_u32_e32 v222, 26, v196
	v_add_u32_e32 v224, 28, v196
	v_add_u32_e32 v226, 30, v196
	v_lshlrev_b64 v[196:197], 12, v[196:197]
	v_ashrrev_i32_e32 v199, 31, v198
	v_ashrrev_i32_e32 v201, 31, v200
	v_ashrrev_i32_e32 v203, 31, v202
	v_ashrrev_i32_e32 v205, 31, v204
	v_ashrrev_i32_e32 v207, 31, v206
	v_ashrrev_i32_e32 v209, 31, v208
	v_ashrrev_i32_e32 v211, 31, v210
	v_ashrrev_i32_e32 v213, 31, v212
	v_ashrrev_i32_e32 v215, 31, v214
	v_ashrrev_i32_e32 v217, 31, v216
	v_ashrrev_i32_e32 v219, 31, v218
	v_ashrrev_i32_e32 v221, 31, v220
	v_ashrrev_i32_e32 v223, 31, v222
	v_ashrrev_i32_e32 v225, 31, v224
	v_ashrrev_i32_e32 v227, 31, v226
	v_lshl_add_u64 v[196:197], v[22:23], 0, v[196:197]
	v_lshlrev_b64 v[198:199], 12, v[198:199]
	v_lshlrev_b64 v[200:201], 12, v[200:201]
	v_lshlrev_b64 v[202:203], 12, v[202:203]
	v_lshlrev_b64 v[204:205], 12, v[204:205]
	v_lshlrev_b64 v[206:207], 12, v[206:207]
	v_lshlrev_b64 v[208:209], 12, v[208:209]
	v_lshlrev_b64 v[210:211], 12, v[210:211]
	v_lshlrev_b64 v[212:213], 12, v[212:213]
	v_lshlrev_b64 v[214:215], 12, v[214:215]
	v_lshlrev_b64 v[216:217], 12, v[216:217]
	v_lshlrev_b64 v[218:219], 12, v[218:219]
	v_lshlrev_b64 v[220:221], 12, v[220:221]
	v_lshlrev_b64 v[222:223], 12, v[222:223]
	v_lshlrev_b64 v[224:225], 12, v[224:225]
	v_lshlrev_b64 v[226:227], 12, v[226:227]
	v_lshl_add_u64 v[198:199], v[22:23], 0, v[198:199]
	v_lshl_add_u64 v[200:201], v[22:23], 0, v[200:201]
	v_lshl_add_u64 v[202:203], v[22:23], 0, v[202:203]
	v_lshl_add_u64 v[204:205], v[22:23], 0, v[204:205]
	v_lshl_add_u64 v[206:207], v[22:23], 0, v[206:207]
	v_lshl_add_u64 v[208:209], v[22:23], 0, v[208:209]
	v_lshl_add_u64 v[210:211], v[22:23], 0, v[210:211]
	v_lshl_add_u64 v[212:213], v[22:23], 0, v[212:213]
	v_lshl_add_u64 v[214:215], v[22:23], 0, v[214:215]
	v_lshl_add_u64 v[216:217], v[22:23], 0, v[216:217]
	v_lshl_add_u64 v[218:219], v[22:23], 0, v[218:219]
	v_lshl_add_u64 v[220:221], v[22:23], 0, v[220:221]
	v_lshl_add_u64 v[222:223], v[22:23], 0, v[222:223]
	v_lshl_add_u64 v[224:225], v[22:23], 0, v[224:225]
	v_lshl_add_u64 v[226:227], v[22:23], 0, v[226:227]
	global_load_dword v228, v[196:197], off nt
	global_load_dword v229, v[198:199], off nt
	global_load_dword v165, v[200:201], off nt
	global_load_dword v166, v[202:203], off nt
	global_load_dword v167, v[204:205], off nt
	global_load_dword v168, v[206:207], off nt
	global_load_dword v169, v[208:209], off nt
	global_load_dword v170, v[210:211], off nt
	global_load_dword v171, v[212:213], off nt
	global_load_dword v172, v[214:215], off nt
	global_load_dword v173, v[216:217], off nt
	global_load_dword v174, v[218:219], off nt
	global_load_dword v175, v[220:221], off nt
	global_load_dword v176, v[222:223], off nt
	global_load_dword v177, v[224:225], off nt
	global_load_dword v196, v[226:227], off nt
	v_add_u32_e32 v27, 0x400, v25
	v_add_u32_e32 v28, 0x800, v25
	v_add_u32_e32 v29, 0xc00, v25
	s_waitcnt vmcnt(30)
; __device__ __forceinline__ unsigned pk2h(float lo, float hi) { const f32x2p_t v = {lo, hi}; const f16x2_t hv = __builtin_convertvector(v, f16x2_t); return __builtin_bit_cast(unsigned, hv); }
; #define LAS __attribute__((address_space(3)))
; __device__ __forceinline__ unsigned pk2(float lo, float hi) { f32x2_t v = {lo, hi}; bf16x2_t b = __builtin_convertvector(v, bf16x2_t); return __builtin_bit_cast(unsigned, b); }
; __device__ __forceinline__ void conv_item(const float* W, int K, int N, bf16* WT, const float* gain, int mapmode, bool f16, LAS float* scr, int item, int lane) {
;     ...
;     for (int i = 0; i < 32; ++i) { const int kk = 2 * i + (lane >> 5); float v = __builtin_nontemporal_load(W + (size_t)(k0 + kk) * N + n0 + (lane & 31)); if (gain) v *= gain[k0 + kk]; scr[kk * 33 + (lane & 31)] = v; }
;     asm volatile("s_waitcnt lgkmcnt(0)" ::: "memory");
;     const int c = lane & 7;
; #pragma unroll
;     for (int j = 0; j < 4; ++j) { const int nl = (lane >> 3) + 8 * j; int n = n0 + nl;
;         if (mapmode == 1) { n = n < DFF ? (n / 128) * 256 + (n % 128) : ((n - DFF) / 128) * 256 + 128 + ((n - DFF) % 128); }
;         const LAS float* s = scr + (8 * c) * 33 + nl;
;         u32x4 o; if (f16) { o.x = pg8::pk2h(s[0 * 33], s[1 * 33]); o.y = pg8::pk2h(s[2 * 33], s[3 * 33]); o.z = pg8::pk2h(s[4 * 33], s[5 * 33]); o.w = pg8::pk2h(s[6 * 33], s[7 * 33]); }
;         else { o.x = pk2(s[0 * 33], s[1 * 33]); o.y = pk2(s[2 * 33], s[3 * 33]); o.z = pk2(s[4 * 33], s[5 * 33]); o.w = pk2(s[6 * 33], s[7 * 33]); }
;         *(u32x4*)(WT + (size_t)n * K + k0 + 8 * c) = o; }
;     asm volatile("s_waitcnt lgkmcnt(0)" ::: "memory");
	ds_write2_b32 v25, v58, v59 offset1:66
	s_waitcnt vmcnt(28)
	ds_write2_b32 v25, v83, v84 offset0:132 offset1:198
	s_waitcnt vmcnt(26)
	ds_write2_b32 v27, v85, v86 offset0:8 offset1:74
	s_waitcnt vmcnt(24)
	ds_write2_b32 v27, v87, v88 offset0:140 offset1:206
	s_waitcnt vmcnt(22)
	ds_write2_b32 v28, v89, v90 offset0:16 offset1:82
	s_waitcnt vmcnt(20)
	ds_write2_b32 v28, v91, v92 offset0:148 offset1:214
	s_waitcnt vmcnt(18)
	ds_write2_b32 v29, v93, v94 offset0:24 offset1:90
	s_waitcnt vmcnt(16)
	ds_write2_b32 v29, v95, v26 offset0:156 offset1:222
	v_add_u32_e32 v25, 0x1080, v25
	v_add_u32_e32 v27, 0x400, v25
	v_add_u32_e32 v28, 0x800, v25
	v_add_u32_e32 v29, 0xc00, v25
	s_waitcnt vmcnt(14)
	ds_write2_b32 v25, v228, v229 offset1:66
	s_waitcnt vmcnt(12)
	ds_write2_b32 v25, v165, v166 offset0:132 offset1:198
	s_waitcnt vmcnt(10)
	ds_write2_b32 v27, v167, v168 offset0:8 offset1:74
	s_waitcnt vmcnt(8)
	ds_write2_b32 v27, v169, v170 offset0:140 offset1:206
	s_waitcnt vmcnt(6)
	ds_write2_b32 v28, v171, v172 offset0:16 offset1:82
	s_waitcnt vmcnt(4)
	ds_write2_b32 v28, v173, v174 offset0:148 offset1:214
	s_waitcnt vmcnt(2)
	ds_write2_b32 v29, v175, v176 offset0:24 offset1:90
	s_waitcnt vmcnt(0)
	ds_write2_b32 v29, v177, v196 offset0:156 offset1:222
	v_add_u32_e32 v25, 0x1080, v25
	s_add_i32 s5, s5, 32
	s_waitcnt lgkmcnt(0)
	ds_read2_b32 v[28:29], v60 offset0:33 offset1:41
	ds_read2_b32 v[30:31], v60 offset1:8
	ds_read2_b32 v[32:33], v60 offset0:66 offset1:74
	ds_read2_b32 v[34:35], v60 offset0:99 offset1:107
	ds_read2_b32 v[36:37], v60 offset0:132 offset1:140
	ds_read2_b32 v[38:39], v60 offset0:165 offset1:173
	ds_read2_b32 v[40:41], v60 offset0:198 offset1:206
	ds_read2_b32 v[42:43], v60 offset0:231 offset1:239
	v_or_b32_e32 v44, s4, v3
	s_ashr_i32 s11, s10, 31
	v_ashrrev_i32_e32 v45, 31, v44
	v_lshl_add_u64 v[26:27], s[10:11], 1, v[20:21]
	v_lshlrev_b64 v[44:45], 10, v[44:45]
	s_waitcnt lgkmcnt(6)
	v_cvt_pk_bf16_f32 v22, v30, v28
	s_waitcnt lgkmcnt(4)
	v_cvt_pk_bf16_f32 v23, v32, v34
	s_waitcnt lgkmcnt(2)
	v_cvt_pk_bf16_f32 v24, v36, v38
	s_waitcnt lgkmcnt(0)
	v_cvt_pk_bf16_f32 v25, v40, v42
	v_lshl_add_u64 v[44:45], v[26:27], 0, v[44:45]
	v_or_b32_e32 v28, s4, v61
	global_store_dwordx4 v[44:45], v[22:25], off
	v_or_b32_e32 v44, s4, v62
	v_ashrrev_i32_e32 v45, 31, v44
	v_cvt_pk_bf16_f32 v22, v31, v29
	v_ashrrev_i32_e32 v29, 31, v28
	v_lshlrev_b64 v[28:29], 10, v[28:29]
	v_cvt_pk_bf16_f32 v23, v33, v35
	v_cvt_pk_bf16_f32 v24, v37, v39
	v_cvt_pk_bf16_f32 v25, v41, v43
	v_lshl_add_u64 v[28:29], v[26:27], 0, v[28:29]
	global_store_dwordx4 v[28:29], v[22:25], off
	ds_read2_b32 v[28:29], v60 offset0:49 offset1:57
	ds_read2_b32 v[30:31], v60 offset0:16 offset1:24
	ds_read2_b32 v[32:33], v60 offset0:82 offset1:90
	ds_read2_b32 v[34:35], v60 offset0:115 offset1:123
	ds_read2_b32 v[36:37], v60 offset0:148 offset1:156
	ds_read2_b32 v[38:39], v60 offset0:181 offset1:189
	ds_read2_b32 v[40:41], v60 offset0:214 offset1:222
	ds_read2_b32 v[42:43], v60 offset0:247 offset1:255
	v_lshlrev_b64 v[44:45], 10, v[44:45]
	s_waitcnt lgkmcnt(6)
	v_cvt_pk_bf16_f32 v22, v30, v28
	s_waitcnt lgkmcnt(4)
	v_cvt_pk_bf16_f32 v23, v32, v34
	s_waitcnt lgkmcnt(2)
	v_cvt_pk_bf16_f32 v24, v36, v38
	s_waitcnt lgkmcnt(0)
	v_cvt_pk_bf16_f32 v25, v40, v42
	v_lshl_add_u64 v[44:45], v[26:27], 0, v[44:45]
	v_or_b32_e32 v28, s4, v63
	global_store_dwordx4 v[44:45], v[22:25], off
	s_add_i32 s13, s13, s24
	s_cmpk_gt_i32 s13, 0xff
	v_cvt_pk_bf16_f32 v22, v31, v29
	v_ashrrev_i32_e32 v29, 31, v28
	v_lshlrev_b64 v[28:29], 10, v[28:29]
	v_cvt_pk_bf16_f32 v23, v33, v35
	v_cvt_pk_bf16_f32 v24, v37, v39
	v_cvt_pk_bf16_f32 v25, v41, v43
	v_lshl_add_u64 v[26:27], v[26:27], 0, v[28:29]
	global_store_dwordx4 v[26:27], v[22:25], off
	s_waitcnt lgkmcnt(0)
	s_cbranch_scc0 .LBB0_136

; __device__ __forceinline__ void conv_item(const float* W, int K, int N, bf16* WT, const float* gain, int mapmode, bool f16, LAS float* scr, int item, int lane) {
;     ...
; #pragma unroll 16
;     for (int i = 0; i < 32; ++i) { const int kk = 2 * i + (lane >> 5); float v = __builtin_nontemporal_load(W + (size_t)(k0 + kk) * N + n0 + (lane & 31)); if (gain) v *= gain[k0 + kk]; scr[kk * 33 + (lane & 31)] = v; }
.LBB0_195:
	v_add_u32_e32 v26, s5, v24
	v_ashrrev_i32_e32 v27, 31, v26
	v_add_u32_e32 v28, 2, v26
	v_add_u32_e32 v30, 4, v26
	v_add_u32_e32 v32, 6, v26
	v_add_u32_e32 v34, 8, v26
	v_add_u32_e32 v36, 10, v26
	v_add_u32_e32 v38, 12, v26
	v_add_u32_e32 v40, 14, v26
	v_add_u32_e32 v42, 16, v26
	v_add_u32_e32 v44, 18, v26
	v_add_u32_e32 v46, 20, v26
	v_add_u32_e32 v48, 22, v26
	v_add_u32_e32 v50, 24, v26
	v_add_u32_e32 v52, 26, v26
	v_add_u32_e32 v54, 28, v26
	v_add_u32_e32 v56, 30, v26
	v_lshlrev_b64 v[26:27], 12, v[26:27]
	v_ashrrev_i32_e32 v29, 31, v28
	v_ashrrev_i32_e32 v31, 31, v30
	v_ashrrev_i32_e32 v33, 31, v32
	v_ashrrev_i32_e32 v35, 31, v34
	v_ashrrev_i32_e32 v37, 31, v36
	v_ashrrev_i32_e32 v39, 31, v38
	v_ashrrev_i32_e32 v41, 31, v40
	v_ashrrev_i32_e32 v43, 31, v42
	v_ashrrev_i32_e32 v45, 31, v44
	v_ashrrev_i32_e32 v47, 31, v46
	v_ashrrev_i32_e32 v49, 31, v48
	v_ashrrev_i32_e32 v51, 31, v50
	v_ashrrev_i32_e32 v53, 31, v52
	v_ashrrev_i32_e32 v55, 31, v54
	v_ashrrev_i32_e32 v57, 31, v56
	v_lshl_add_u64 v[26:27], v[22:23], 0, v[26:27]
	v_lshlrev_b64 v[28:29], 12, v[28:29]
	v_lshlrev_b64 v[30:31], 12, v[30:31]
	v_lshlrev_b64 v[32:33], 12, v[32:33]
	v_lshlrev_b64 v[34:35], 12, v[34:35]
	v_lshlrev_b64 v[36:37], 12, v[36:37]
	v_lshlrev_b64 v[38:39], 12, v[38:39]
	v_lshlrev_b64 v[40:41], 12, v[40:41]
	v_lshlrev_b64 v[42:43], 12, v[42:43]
	v_lshlrev_b64 v[44:45], 12, v[44:45]
	v_lshlrev_b64 v[46:47], 12, v[46:47]
	v_lshlrev_b64 v[48:49], 12, v[48:49]
	v_lshlrev_b64 v[50:51], 12, v[50:51]
	v_lshlrev_b64 v[52:53], 12, v[52:53]
	v_lshlrev_b64 v[54:55], 12, v[54:55]
	v_lshlrev_b64 v[56:57], 12, v[56:57]
	v_lshl_add_u64 v[28:29], v[22:23], 0, v[28:29]
	v_lshl_add_u64 v[30:31], v[22:23], 0, v[30:31]
	v_lshl_add_u64 v[32:33], v[22:23], 0, v[32:33]
	v_lshl_add_u64 v[34:35], v[22:23], 0, v[34:35]
	v_lshl_add_u64 v[36:37], v[22:23], 0, v[36:37]
	v_lshl_add_u64 v[38:39], v[22:23], 0, v[38:39]
	v_lshl_add_u64 v[40:41], v[22:23], 0, v[40:41]
	v_lshl_add_u64 v[42:43], v[22:23], 0, v[42:43]
	v_lshl_add_u64 v[44:45], v[22:23], 0, v[44:45]
	v_lshl_add_u64 v[46:47], v[22:23], 0, v[46:47]
	v_lshl_add_u64 v[48:49], v[22:23], 0, v[48:49]
	v_lshl_add_u64 v[50:51], v[22:23], 0, v[50:51]
	v_lshl_add_u64 v[52:53], v[22:23], 0, v[52:53]
	v_lshl_add_u64 v[54:55], v[22:23], 0, v[54:55]
	v_lshl_add_u64 v[56:57], v[22:23], 0, v[56:57]
	global_load_dword v58, v[26:27], off nt
	global_load_dword v59, v[28:29], off nt
	global_load_dword v83, v[30:31], off nt
	global_load_dword v84, v[32:33], off nt
	global_load_dword v85, v[34:35], off nt
	global_load_dword v86, v[36:37], off nt
	global_load_dword v87, v[38:39], off nt
	global_load_dword v88, v[40:41], off nt
	global_load_dword v89, v[42:43], off nt
	global_load_dword v90, v[44:45], off nt
	global_load_dword v91, v[46:47], off nt
	global_load_dword v92, v[48:49], off nt
	global_load_dword v93, v[50:51], off nt
	global_load_dword v94, v[52:53], off nt
	global_load_dword v95, v[54:55], off nt
	global_load_dword v26, v[56:57], off nt
	s_add_i32 s5, s5, 32
	v_add_u32_e32 v196, s5, v24
	v_ashrrev_i32_e32 v197, 31, v196
	v_add_u32_e32 v198, 2, v196
	v_add_u32_e32 v200, 4, v196
	v_add_u32_e32 v202, 6, v196
	v_add_u32_e32 v204, 8, v196
	v_add_u32_e32 v206, 10, v196
	v_add_u32_e32 v208, 12, v196
	v_add_u32_e32 v210, 14, v196
	v_add_u32_e32 v212, 16, v196
	v_add_u32_e32 v214, 18, v196
	v_add_u32_e32 v216, 20, v196
	v_add_u32_e32 v218, 22, v196
	v_add_u32_e32 v220, 24, v196
	v_add_u32_e32 v222, 26, v196
	v_add_u32_e32 v224, 28, v196
	v_add_u32_e32 v226, 30, v196
	v_lshlrev_b64 v[196:197], 12, v[196:197]
	v_ashrrev_i32_e32 v199, 31, v198
	v_ashrrev_i32_e32 v201, 31, v200
	v_ashrrev_i32_e32 v203, 31, v202
	v_ashrrev_i32_e32 v205, 31, v204
	v_ashrrev_i32_e32 v207, 31, v206
	v_ashrrev_i32_e32 v209, 31, v208
	v_ashrrev_i32_e32 v211, 31, v210
	v_ashrrev_i32_e32 v213, 31, v212
	v_ashrrev_i32_e32 v215, 31, v214
	v_ashrrev_i32_e32 v217, 31, v216
	v_ashrrev_i32_e32 v219, 31, v218
	v_ashrrev_i32_e32 v221, 31, v220
	v_ashrrev_i32_e32 v223, 31, v222
	v_ashrrev_i32_e32 v225, 31, v224
	v_ashrrev_i32_e32 v227, 31, v226
	v_lshl_add_u64 v[196:197], v[22:23], 0, v[196:197]
	v_lshlrev_b64 v[198:199], 12, v[198:199]
	v_lshlrev_b64 v[200:201], 12, v[200:201]
	v_lshlrev_b64 v[202:203], 12, v[202:203]
	v_lshlrev_b64 v[204:205], 12, v[204:205]
	v_lshlrev_b64 v[206:207], 12, v[206:207]
	v_lshlrev_b64 v[208:209], 12, v[208:209]
	v_lshlrev_b64 v[210:211], 12, v[210:211]
	v_lshlrev_b64 v[212:213], 12, v[212:213]
	v_lshlrev_b64 v[214:215], 12, v[214:215]
	v_lshlrev_b64 v[216:217], 12, v[216:217]
	v_lshlrev_b64 v[218:219], 12, v[218:219]
	v_lshlrev_b64 v[220:221], 12, v[220:221]
	v_lshlrev_b64 v[222:223], 12, v[222:223]
	v_lshlrev_b64 v[224:225], 12, v[224:225]
	v_lshlrev_b64 v[226:227], 12, v[226:227]
	v_lshl_add_u64 v[198:199], v[22:23], 0, v[198:199]
	v_lshl_add_u64 v[200:201], v[22:23], 0, v[200:201]
	v_lshl_add_u64 v[202:203], v[22:23], 0, v[202:203]
	v_lshl_add_u64 v[204:205], v[22:23], 0, v[204:205]
	v_lshl_add_u64 v[206:207], v[22:23], 0, v[206:207]
	v_lshl_add_u64 v[208:209], v[22:23], 0, v[208:209]
	v_lshl_add_u64 v[210:211], v[22:23], 0, v[210:211]
	v_lshl_add_u64 v[212:213], v[22:23], 0, v[212:213]
	v_lshl_add_u64 v[214:215], v[22:23], 0, v[214:215]
	v_lshl_add_u64 v[216:217], v[22:23], 0, v[216:217]
	v_lshl_add_u64 v[218:219], v[22:23], 0, v[218:219]
	v_lshl_add_u64 v[220:221], v[22:23], 0, v[220:221]
	v_lshl_add_u64 v[222:223], v[22:23], 0, v[222:223]
	v_lshl_add_u64 v[224:225], v[22:23], 0, v[224:225]
	v_lshl_add_u64 v[226:227], v[22:23], 0, v[226:227]
	global_load_dword v228, v[196:197], off nt
	global_load_dword v229, v[198:199], off nt
	global_load_dword v165, v[200:201], off nt
	global_load_dword v166, v[202:203], off nt
	global_load_dword v167, v[204:205], off nt
	global_load_dword v168, v[206:207], off nt
	global_load_dword v169, v[208:209], off nt
	global_load_dword v170, v[210:211], off nt
	global_load_dword v171, v[212:213], off nt
	global_load_dword v172, v[214:215], off nt
	global_load_dword v173, v[216:217], off nt
	global_load_dword v174, v[218:219], off nt
	global_load_dword v175, v[220:221], off nt
	global_load_dword v176, v[222:223], off nt
	global_load_dword v177, v[224:225], off nt
	global_load_dword v196, v[226:227], off nt
	v_add_u32_e32 v27, 0x400, v25
	v_add_u32_e32 v28, 0x800, v25
	v_add_u32_e32 v29, 0xc00, v25
	s_waitcnt vmcnt(30)
; __device__ __forceinline__ unsigned pk2h(float lo, float hi) { const f32x2p_t v = {lo, hi}; const f16x2_t hv = __builtin_convertvector(v, f16x2_t); return __builtin_bit_cast(unsigned, hv); }
; #define LAS __attribute__((address_space(3)))
; __device__ __forceinline__ unsigned pk2(float lo, float hi) { f32x2_t v = {lo, hi}; bf16x2_t b = __builtin_convertvector(v, bf16x2_t); return __builtin_bit_cast(unsigned, b); }
; __device__ __forceinline__ void conv_item(const float* W, int K, int N, bf16* WT, const float* gain, int mapmode, bool f16, LAS float* scr, int item, int lane) {
;     ...
;     for (int i = 0; i < 32; ++i) { const int kk = 2 * i + (lane >> 5); float v = __builtin_nontemporal_load(W + (size_t)(k0 + kk) * N + n0 + (lane & 31)); if (gain) v *= gain[k0 + kk]; scr[kk * 33 + (lane & 31)] = v; }
;     asm volatile("s_waitcnt lgkmcnt(0)" ::: "memory");
;     const int c = lane & 7;
; #pragma unroll
;     for (int j = 0; j < 4; ++j) { const int nl = (lane >> 3) + 8 * j; int n = n0 + nl;
;         if (mapmode == 1) { n = n < DFF ? (n / 128) * 256 + (n % 128) : ((n - DFF) / 128) * 256 + 128 + ((n - DFF) % 128); }
;         const LAS float* s = scr + (8 * c) * 33 + nl;
;         u32x4 o; if (f16) { o.x = pg8::pk2h(s[0 * 33], s[1 * 33]); o.y = pg8::pk2h(s[2 * 33], s[3 * 33]); o.z = pg8::pk2h(s[4 * 33], s[5 * 33]); o.w = pg8::pk2h(s[6 * 33], s[7 * 33]); }
;         else { o.x = pk2(s[0 * 33], s[1 * 33]); o.y = pk2(s[2 * 33], s[3 * 33]); o.z = pk2(s[4 * 33], s[5 * 33]); o.w = pk2(s[6 * 33], s[7 * 33]); }
;         *(u32x4*)(WT + (size_t)n * K + k0 + 8 * c) = o; }
;     asm volatile("s_waitcnt lgkmcnt(0)" ::: "memory");
	ds_write2_b32 v25, v58, v59 offset1:66
	s_waitcnt vmcnt(28)
	ds_write2_b32 v25, v83, v84 offset0:132 offset1:198
	s_waitcnt vmcnt(26)
	ds_write2_b32 v27, v85, v86 offset0:8 offset1:74
	s_waitcnt vmcnt(24)
	ds_write2_b32 v27, v87, v88 offset0:140 offset1:206
	s_waitcnt vmcnt(22)
	ds_write2_b32 v28, v89, v90 offset0:16 offset1:82
	s_waitcnt vmcnt(20)
	ds_write2_b32 v28, v91, v92 offset0:148 offset1:214
	s_waitcnt vmcnt(18)
	ds_write2_b32 v29, v93, v94 offset0:24 offset1:90
	s_waitcnt vmcnt(16)
	ds_write2_b32 v29, v95, v26 offset0:156 offset1:222
	v_add_u32_e32 v25, 0x1080, v25
	v_add_u32_e32 v27, 0x400, v25
	v_add_u32_e32 v28, 0x800, v25
	v_add_u32_e32 v29, 0xc00, v25
	s_waitcnt vmcnt(14)
	ds_write2_b32 v25, v228, v229 offset1:66
	s_waitcnt vmcnt(12)
	ds_write2_b32 v25, v165, v166 offset0:132 offset1:198
	s_waitcnt vmcnt(10)
	ds_write2_b32 v27, v167, v168 offset0:8 offset1:74
	s_waitcnt vmcnt(8)
	ds_write2_b32 v27, v169, v170 offset0:140 offset1:206
	s_waitcnt vmcnt(6)
	ds_write2_b32 v28, v171, v172 offset0:16 offset1:82
	s_waitcnt vmcnt(4)
	ds_write2_b32 v28, v173, v174 offset0:148 offset1:214
	s_waitcnt vmcnt(2)
	ds_write2_b32 v29, v175, v176 offset0:24 offset1:90
	s_waitcnt vmcnt(0)
	ds_write2_b32 v29, v177, v196 offset0:156 offset1:222
	v_add_u32_e32 v25, 0x1080, v25
	s_add_i32 s5, s5, 32
	s_waitcnt lgkmcnt(0)
	ds_read2_b32 v[28:29], v60 offset0:33 offset1:41
	ds_read2_b32 v[30:31], v60 offset1:8
	ds_read2_b32 v[32:33], v60 offset0:66 offset1:74
	ds_read2_b32 v[34:35], v60 offset0:99 offset1:107
	ds_read2_b32 v[36:37], v60 offset0:132 offset1:140
	ds_read2_b32 v[38:39], v60 offset0:165 offset1:173
	ds_read2_b32 v[40:41], v60 offset0:198 offset1:206
	ds_read2_b32 v[42:43], v60 offset0:231 offset1:239
	v_or_b32_e32 v44, s4, v3
	s_ashr_i32 s11, s10, 31
	v_mul_lo_u32 v44, v44, s40
	v_lshl_add_u64 v[26:27], s[10:11], 1, v[20:21]
	s_waitcnt lgkmcnt(6)
	v_cvt_pk_bf16_f32 v22, v30, v28
	v_ashrrev_i32_e32 v45, 31, v44
	v_or_b32_e32 v28, s4, v61
	s_waitcnt lgkmcnt(4)
	v_cvt_pk_bf16_f32 v23, v32, v34
	s_waitcnt lgkmcnt(2)
	v_cvt_pk_bf16_f32 v24, v36, v38
	s_waitcnt lgkmcnt(0)
	v_cvt_pk_bf16_f32 v25, v40, v42
	v_lshl_add_u64 v[44:45], v[44:45], 1, v[26:27]
	v_mul_lo_u32 v28, v28, s40
	global_store_dwordx4 v[44:45], v[22:25], off
	v_or_b32_e32 v44, s4, v62
	v_mul_lo_u32 v44, v44, s40
	v_cvt_pk_bf16_f32 v22, v31, v29
	v_ashrrev_i32_e32 v29, 31, v28
	v_cvt_pk_bf16_f32 v23, v33, v35
	v_cvt_pk_bf16_f32 v24, v37, v39
	v_cvt_pk_bf16_f32 v25, v41, v43
	v_lshl_add_u64 v[28:29], v[28:29], 1, v[26:27]
	global_store_dwordx4 v[28:29], v[22:25], off
	ds_read2_b32 v[28:29], v60 offset0:49 offset1:57
	ds_read2_b32 v[30:31], v60 offset0:16 offset1:24
	ds_read2_b32 v[32:33], v60 offset0:82 offset1:90
	ds_read2_b32 v[34:35], v60 offset0:115 offset1:123
	ds_read2_b32 v[36:37], v60 offset0:148 offset1:156
	ds_read2_b32 v[38:39], v60 offset0:181 offset1:189
	ds_read2_b32 v[40:41], v60 offset0:214 offset1:222
	ds_read2_b32 v[42:43], v60 offset0:247 offset1:255
	s_waitcnt lgkmcnt(6)
	v_cvt_pk_bf16_f32 v22, v30, v28
	v_ashrrev_i32_e32 v45, 31, v44
	v_or_b32_e32 v28, s4, v63
	s_waitcnt lgkmcnt(4)
	v_cvt_pk_bf16_f32 v23, v32, v34
	s_waitcnt lgkmcnt(2)
	v_cvt_pk_bf16_f32 v24, v36, v38
	s_waitcnt lgkmcnt(0)
	v_cvt_pk_bf16_f32 v25, v40, v42
	v_lshl_add_u64 v[44:45], v[44:45], 1, v[26:27]
	v_mul_lo_u32 v28, v28, s40
	global_store_dwordx4 v[44:45], v[22:25], off
	s_add_i32 s13, s13, s24
	s_cmpk_gt_i32 s13, 0x57f
	v_cvt_pk_bf16_f32 v22, v31, v29
	v_ashrrev_i32_e32 v29, 31, v28
	v_cvt_pk_bf16_f32 v23, v33, v35
	v_cvt_pk_bf16_f32 v24, v37, v39
	v_cvt_pk_bf16_f32 v25, v41, v43
	v_lshl_add_u64 v[26:27], v[28:29], 1, v[26:27]
	global_store_dwordx4 v[26:27], v[22:25], off
	s_waitcnt lgkmcnt(0)
	s_cbranch_scc0 .LBB0_194
	s_branch .LBB0_59
